# GEMM3 stagger variant: odd XCDs (blockIdx bit0) process the half-height unit first
# speedup vs baseline: 1.0051x; 1.0029x over previous
.Lmy_g3_cnt:
	s_add_i32 s100, s100, 1
	s_add_i32 s99, s99, s84
	s_cmp_lt_i32 s99, s55
	s_cbranch_scc1 .Lmy_g3_cnt
	s_mov_b32 s98, s100
	s_mul_i32 s101, s100, s84
	s_sub_i32 s99, s99, s84
	s_bitcmp1_b32 s75, 0
	s_cbranch_scc0 .Lmy_g3_go
	s_cmp_lt_i32 s99, s54
	s_cbranch_scc1 .Lmy_g3_go
	s_mov_b32 s75, s99
